# static priority raise in the DMA GEMM mainloops at level 3 instead of 1
# baseline (speedup 1.0000x reference)
.LBB0_463:
	s_ashr_i32 s0, s12, 3
	s_mul_hi_i32 s1, s0, 0x66666667
	s_lshr_b32 s13, s1, 31
	s_ashr_i32 s1, s1, 4
	s_add_i32 s1, s1, s13
	s_mul_i32 s13, s1, 40
	s_sub_i32 s0, s0, s13
	s_and_b32 s22, s0, 7
	s_mul_i32 s1, s1, 5
	s_ashr_i32 s0, s0, 3
	s_lshl_b32 s13, s12, 3
	s_add_i32 s1, s1, s0
	s_and_b32 s13, s13, 56
	s_lshl_b32 s0, s1, 7
	s_or_b32 s13, s22, s13
	s_add_i32 s22, s0, 0x100
	s_cmp_lt_i32 s1, 6
	s_cselect_b32 s0, s0, s22
	s_lshl_b32 s1, s13, 18
	v_readlane_b32 s22, v251, 31
	v_mov_b32_e32 v36, v178
	v_readlane_b32 s23, v251, 32
	s_add_u32 s22, s22, s1
	s_addc_u32 s23, s23, 0
	v_ashrrev_i32_e32 v34, 3, v36
	s_ashr_i32 s1, s0, 31
	v_lshlrev_b32_e32 v0, 3, v36
	v_ashrrev_i32_e32 v35, 31, v34
	s_lshl_b64 s[24:25], s[0:1], 11
	v_and_b32_e32 v37, 56, v0
	v_lshlrev_b64 v[2:3], 11, v[34:35]
	s_add_u32 s24, s92, s24
	v_lshl_add_u64 v[4:5], s[22:23], 0, v[2:3]
	v_lshlrev_b32_e32 v0, 1, v37
	s_addc_u32 s25, s93, s25
	v_lshl_add_u64 v[68:69], v[4:5], 0, v[0:1]
	v_lshl_add_u64 v[2:3], s[24:25], 0, v[2:3]
	v_lshl_add_u64 v[70:71], v[2:3], 0, v[0:1]
	v_and_b32_e32 v0, 7, v36
	v_bfe_u32 v66, v36, 4, 3
	v_xor_b32_e32 v66, v66, v0
	v_sub_u32_e32 v66, v66, v0
	v_lshlrev_b32_e32 v66, 4, v66
	v_ashrrev_i32_e32 v67, 31, v66
	v_lshl_add_u64 v[68:69], v[68:69], 0, v[66:67]
	v_lshl_add_u64 v[70:71], v[70:71], 0, v[66:67]
	v_add_co_u32_e32 v72, vcc, s73, v68
	s_nop 1
	v_addc_co_u32_e32 v73, vcc, 0, v69, vcc
	v_add_co_u32_e32 v74, vcc, s73, v70
	s_nop 1
	v_addc_co_u32_e32 v75, vcc, 0, v71, vcc
	v_add_co_u32_e32 v76, vcc, s52, v68
	s_nop 1
	v_addc_co_u32_e32 v77, vcc, 0, v69, vcc
	v_add_co_u32_e32 v78, vcc, s52, v70
	s_nop 1
	v_addc_co_u32_e32 v79, vcc, 0, v71, vcc
	v_add_co_u32_e32 v80, vcc, s53, v68
	s_nop 1
	v_addc_co_u32_e32 v81, vcc, 0, v69, vcc
	v_add_co_u32_e32 v82, vcc, s53, v70
	s_nop 1
	v_addc_co_u32_e32 v83, vcc, 0, v71, vcc
	v_and_b32_e32 v0, 31, v36
	v_bfe_u32 v66, v36, 5, 1
	v_bfe_u32 v67, v36, 1, 3
	v_xor_b32_e32 v66, v66, v67
	v_lshlrev_b32_e32 v66, 4, v66
	v_lshl_add_u32 v66, v0, 7, v66
	v_bfe_u32 v67, v36, 7, 1
	v_lshl_add_u32 v86, v67, 13, v66
	v_bfe_u32 v67, v36, 6, 1
	v_lshl_add_u32 v90, v67, 13, v66
	v_add_u32_e32 v90, 0x4000, v90
	v_xor_b32_e32 v87, 32, v86
	v_xor_b32_e32 v91, 32, v90
	v_xor_b32_e32 v88, 64, v86
	v_xor_b32_e32 v92, 64, v90
	v_xor_b32_e32 v89, 96, v86
	v_xor_b32_e32 v93, 96, v90
	v_lshrrev_b32_e32 v66, 6, v36
	v_lshlrev_b32_e32 v66, 10, v66
	s_nop 1
	v_readfirstlane_b32 s14, v66
	s_movk_i32 s1, 0x14c0
	s_mov_b32 s27, 0
	s_lshl_b32 s13, s13, 7
	v_readlane_b32 s15, v251, 0
	s_cmpk_lt_u32 s15, 0x100
	s_cbranch_scc1 .Lgp_g0
	s_setprio 3

.LBB0_582:
	s_add_i32 s0, s25, 0xfffffc00
	s_lshr_b32 s1, s0, 1
	s_lshl_b32 s0, s25, 7
	s_and_b32 s0, s0, 0x80
	s_waitcnt vmcnt(12)
	v_mov_b32_e32 v36, v178
	s_or_b32 s0, s0, 0x300
	s_lshl_b32 s12, s1, 18
	v_readlane_b32 s22, v251, 31
	v_readlane_b32 s23, v251, 32
	v_ashrrev_i32_e32 v34, 3, v36
	s_add_u32 s12, s22, s12
	v_lshlrev_b32_e32 v0, 3, v36
	v_ashrrev_i32_e32 v35, 31, v34
	s_addc_u32 s13, s23, 0
	s_lshl_b32 s22, s0, 11
	v_and_b32_e32 v37, 56, v0
	s_waitcnt vmcnt(5)
	v_lshlrev_b64 v[2:3], 11, v[34:35]
	s_add_u32 s22, s92, s22
	v_lshl_add_u64 v[4:5], s[12:13], 0, v[2:3]
	v_lshlrev_b32_e32 v0, 1, v37
	s_addc_u32 s23, s93, 0
	v_lshl_add_u64 v[68:69], v[4:5], 0, v[0:1]
	v_lshl_add_u64 v[2:3], s[22:23], 0, v[2:3]
	v_lshl_add_u64 v[70:71], v[2:3], 0, v[0:1]
	v_and_b32_e32 v0, 7, v36
	v_bfe_u32 v66, v36, 4, 3
	v_xor_b32_e32 v66, v66, v0
	v_sub_u32_e32 v66, v66, v0
	v_lshlrev_b32_e32 v66, 4, v66
	v_ashrrev_i32_e32 v67, 31, v66
	v_lshl_add_u64 v[68:69], v[68:69], 0, v[66:67]
	v_lshl_add_u64 v[70:71], v[70:71], 0, v[66:67]
	v_add_co_u32_e32 v72, vcc, s73, v68
	s_nop 1
	v_addc_co_u32_e32 v73, vcc, 0, v69, vcc
	v_add_co_u32_e32 v74, vcc, s73, v70
	s_nop 1
	v_addc_co_u32_e32 v75, vcc, 0, v71, vcc
	v_add_co_u32_e32 v76, vcc, s52, v68
	s_nop 1
	v_addc_co_u32_e32 v77, vcc, 0, v69, vcc
	v_add_co_u32_e32 v78, vcc, s52, v70
	s_nop 1
	v_addc_co_u32_e32 v79, vcc, 0, v71, vcc
	v_add_co_u32_e32 v80, vcc, s53, v68
	s_nop 1
	v_addc_co_u32_e32 v81, vcc, 0, v69, vcc
	v_add_co_u32_e32 v82, vcc, s53, v70
	s_nop 1
	v_addc_co_u32_e32 v83, vcc, 0, v71, vcc
	v_and_b32_e32 v0, 31, v36
	v_bfe_u32 v66, v36, 5, 1
	v_bfe_u32 v67, v36, 1, 3
	v_xor_b32_e32 v66, v66, v67
	v_lshlrev_b32_e32 v66, 4, v66
	v_lshl_add_u32 v66, v0, 7, v66
	v_bfe_u32 v67, v36, 7, 1
	v_lshl_add_u32 v86, v67, 13, v66
	v_bfe_u32 v67, v36, 6, 1
	v_lshl_add_u32 v90, v67, 13, v66
	v_add_u32_e32 v90, 0x4000, v90
	v_xor_b32_e32 v87, 32, v86
	v_xor_b32_e32 v91, 32, v90
	v_xor_b32_e32 v88, 64, v86
	v_xor_b32_e32 v92, 64, v90
	v_xor_b32_e32 v89, 96, v86
	v_xor_b32_e32 v93, 96, v90
	v_lshrrev_b32_e32 v66, 6, v36
	v_lshlrev_b32_e32 v66, 10, v66
	s_nop 1
	v_readfirstlane_b32 s14, v66
	s_mov_b32 s12, 0
	s_lshl_b32 s1, s1, 7
	v_readlane_b32 s15, v251, 0
	s_cmpk_lt_u32 s15, 0x100
	s_cbranch_scc1 .Lgp_g1
	s_setprio 3

.LBB0_855:
	s_lshl_b32 s0, s45, 10
	s_waitcnt vmcnt(3)
	v_mov_b32_e32 v6, v178
	s_add_i32 s0, s24, s0
	s_ashr_i32 s1, s0, 31
	v_ashrrev_i32_e32 v34, 3, v6
	v_lshlrev_b32_e32 v0, 3, v6
	v_ashrrev_i32_e32 v35, 31, v34
	s_lshl_b64 s[0:1], s[0:1], 11
	v_and_b32_e32 v36, 56, v0
	v_lshlrev_b64 v[2:3], 11, v[34:35]
	s_add_u32 s0, s92, s0
	v_lshl_add_u64 v[4:5], s[40:41], 0, v[2:3]
	v_lshlrev_b32_e32 v0, 1, v36
	s_addc_u32 s1, s93, s1
	v_lshl_add_u64 v[148:149], v[4:5], 0, v[0:1]
	v_lshl_add_u64 v[2:3], s[0:1], 0, v[2:3]
	v_lshl_add_u64 v[150:151], v[2:3], 0, v[0:1]
	v_and_b32_e32 v0, 7, v178
	v_bfe_u32 v146, v178, 4, 3
	v_xor_b32_e32 v146, v146, v0
	v_sub_u32_e32 v146, v146, v0
	v_lshlrev_b32_e32 v146, 4, v146
	v_ashrrev_i32_e32 v147, 31, v146
	v_lshl_add_u64 v[148:149], v[148:149], 0, v[146:147]
	v_lshl_add_u64 v[150:151], v[150:151], 0, v[146:147]
	v_add_co_u32_e32 v152, vcc, s73, v148
	s_nop 1
	v_addc_co_u32_e32 v153, vcc, 0, v149, vcc
	v_add_co_u32_e32 v154, vcc, s73, v150
	s_nop 1
	v_addc_co_u32_e32 v155, vcc, 0, v151, vcc
	v_add_co_u32_e32 v156, vcc, s52, v148
	s_nop 1
	v_addc_co_u32_e32 v157, vcc, 0, v149, vcc
	v_add_co_u32_e32 v158, vcc, s52, v150
	s_nop 1
	v_addc_co_u32_e32 v159, vcc, 0, v151, vcc
	v_add_co_u32_e32 v160, vcc, s53, v148
	s_nop 1
	v_addc_co_u32_e32 v161, vcc, 0, v149, vcc
	v_add_co_u32_e32 v162, vcc, s53, v150
	s_nop 1
	v_addc_co_u32_e32 v163, vcc, 0, v151, vcc
	v_and_b32_e32 v0, 31, v178
	v_bfe_u32 v146, v178, 5, 1
	v_bfe_u32 v147, v178, 1, 3
	v_xor_b32_e32 v146, v146, v147
	v_lshlrev_b32_e32 v146, 4, v146
	v_lshl_add_u32 v146, v0, 7, v146
	v_bfe_u32 v147, v178, 7, 1
	v_lshl_add_u32 v130, v147, 13, v146
	v_bfe_u32 v147, v178, 6, 1
	v_lshl_add_u32 v134, v147, 13, v146
	v_add_u32_e32 v134, 0x4000, v134
	v_xor_b32_e32 v131, 32, v130
	v_xor_b32_e32 v135, 32, v134
	v_xor_b32_e32 v132, 64, v130
	v_xor_b32_e32 v136, 64, v134
	v_xor_b32_e32 v133, 96, v130
	v_xor_b32_e32 v137, 96, v134
	v_lshrrev_b32_e32 v146, 6, v178
	v_lshlrev_b32_e32 v146, 10, v146
	s_nop 1
	v_readfirstlane_b32 s14, v146
	v_readlane_b32 s15, v251, 0
	s_cmpk_lt_u32 s15, 0x100
	s_cbranch_scc1 .Lgp_ma
	s_setprio 3

.LBB0_909:
	s_lshl_b32 s0, s13, 3
	s_and_b32 s0, s0, 56
	s_bfe_u32 s1, s13, 0x30003
	s_or_b32 s20, s0, s1
	s_lshl_b32 s0, s13, 1
	s_and_b32 s0, s0, 0xffffff80
	s_lshl_b32 s1, s20, 18
	v_readlane_b32 s22, v251, 37
	s_waitcnt vmcnt(12)
	v_mov_b32_e32 v36, v178
	v_readlane_b32 s23, v251, 38
	s_add_u32 s22, s22, s1
	s_addc_u32 s23, s23, 0
	v_ashrrev_i32_e32 v34, 3, v36
	s_ashr_i32 s1, s0, 31
	v_lshlrev_b32_e32 v0, 3, v36
	v_ashrrev_i32_e32 v35, 31, v34
	s_lshl_b64 s[24:25], s[0:1], 11
	v_and_b32_e32 v37, 56, v0
	s_waitcnt vmcnt(5)
	v_lshlrev_b64 v[2:3], 11, v[34:35]
	s_add_u32 s24, s68, s24
	v_lshl_add_u64 v[4:5], s[22:23], 0, v[2:3]
	v_lshlrev_b32_e32 v0, 1, v37
	s_addc_u32 s25, s69, s25
	v_lshl_add_u64 v[68:69], v[4:5], 0, v[0:1]
	v_lshl_add_u64 v[2:3], s[24:25], 0, v[2:3]
	v_lshl_add_u64 v[70:71], v[2:3], 0, v[0:1]
	v_and_b32_e32 v0, 7, v36
	v_bfe_u32 v66, v36, 4, 3
	v_xor_b32_e32 v66, v66, v0
	v_sub_u32_e32 v66, v66, v0
	v_lshlrev_b32_e32 v66, 4, v66
	v_ashrrev_i32_e32 v67, 31, v66
	v_lshl_add_u64 v[68:69], v[68:69], 0, v[66:67]
	v_lshl_add_u64 v[70:71], v[70:71], 0, v[66:67]
	v_add_co_u32_e32 v72, vcc, s73, v68
	s_nop 1
	v_addc_co_u32_e32 v73, vcc, 0, v69, vcc
	v_add_co_u32_e32 v74, vcc, s73, v70
	s_nop 1
	v_addc_co_u32_e32 v75, vcc, 0, v71, vcc
	v_add_co_u32_e32 v76, vcc, s52, v68
	s_nop 1
	v_addc_co_u32_e32 v77, vcc, 0, v69, vcc
	v_add_co_u32_e32 v78, vcc, s52, v70
	s_nop 1
	v_addc_co_u32_e32 v79, vcc, 0, v71, vcc
	v_add_co_u32_e32 v80, vcc, s53, v68
	s_nop 1
	v_addc_co_u32_e32 v81, vcc, 0, v69, vcc
	v_add_co_u32_e32 v82, vcc, s53, v70
	s_nop 1
	v_addc_co_u32_e32 v83, vcc, 0, v71, vcc
	v_and_b32_e32 v0, 31, v36
	v_bfe_u32 v66, v36, 5, 1
	v_bfe_u32 v67, v36, 1, 3
	v_xor_b32_e32 v66, v66, v67
	v_lshlrev_b32_e32 v66, 4, v66
	v_lshl_add_u32 v66, v0, 7, v66
	v_bfe_u32 v67, v36, 7, 1
	v_lshl_add_u32 v86, v67, 13, v66
	v_bfe_u32 v67, v36, 6, 1
	v_lshl_add_u32 v90, v67, 13, v66
	v_add_u32_e32 v90, 0x4000, v90
	v_xor_b32_e32 v87, 32, v86
	v_xor_b32_e32 v91, 32, v90
	v_xor_b32_e32 v88, 64, v86
	v_xor_b32_e32 v92, 64, v90
	v_xor_b32_e32 v89, 96, v86
	v_xor_b32_e32 v93, 96, v90
	v_lshrrev_b32_e32 v66, 6, v36
	v_lshlrev_b32_e32 v66, 10, v66
	s_nop 1
	v_readfirstlane_b32 s14, v66
	s_mov_b32 s21, 0
	s_lshl_b32 s20, s20, 7
	v_readlane_b32 s15, v251, 0
	s_cmpk_lt_u32 s15, 0x100
	s_cbranch_scc1 .Lgp_g2
	s_setprio 3
